# transposed-v epilogue of the w_in GEMM also via per-wave LDS transpose (8 columns x 128 B per store)
# baseline (speedup 1.0000x reference)
; __device__ __forceinline__ unsigned pk2(float lo, float hi) { const v2f_t f = {lo, hi}; const v2bf_t b = __builtin_convertvector(f, v2bf_t); return __builtin_bit_cast(unsigned, b); }
;     __device__ __forceinline__ void operator()(const f32x4 (&acc)[2][2][4][2], const Unit& u, int wr, int wc, int fr, int fq) const {
;     ...
;         if (u.pn >= 2 && u.pn < 6) {
;             const int cb = (u.pn - 2) * 256 + wc * 32 + 8 * fq;
;             bf16_t* vb; int tl, t0;
;             if (u.pm < 64) { vb = vtl + (size_t)(u.pm >> 4) * 1024 * T; tl = T; t0 = (u.pm & 15) * 256; } else { vb = vtc + (size_t)(u.pm - 64) * 1024 * CTXL; tl = CTXL; t0 = 0; }
;             t0 += wr * 64 + fr;
; #pragma unroll
;             for (int ai = 0; ai < 2; ++ai)
; #pragma unroll
;                 for (int m = 0; m < 4; ++m) { bf16_t* tp = vb + t0 + ai * 128 + m * 16;
; #pragma unroll
;                     for (int bj = 0; bj < 2; ++bj)
; #pragma unroll
;                         for (int n = 0; n < 2; ++n) { const f32x4 v = acc[ai][bj][m][n]; const unsigned w0 = pk2(v[0], v[1]), w1 = pk2(v[2], v[3]); const size_t c = (size_t)(cb + bj * 128 + 4 * n) * tl;
;                             tp[c] = (bf16_t)w0; tp[c + tl] = (bf16_t)(w0 >> 16); tp[c + 2 * (size_t)tl] = (bf16_t)w1; tp[c + 3 * (size_t)tl] = (bf16_t)(w1 >> 16); } }
.LBB0_220:
	v_lshl_add_u32 v149, s30, 8, v147
	v_and_b32_e32 v151, 63, v194
	v_lshrrev_b32_e32 v152, 6, v194
	v_and_b32_e32 v153, 15, v194
	v_bfe_u32 v154, v194, 4, 2
	v_lshlrev_b32_e32 v160, 11, v152
	v_add_u32_e32 v160, 0x23410, v160
	v_lshl_add_u32 v161, v154, 9, v160
	v_lshl_add_u32 v161, v153, 1, v161
	v_lshrrev_b32_e32 v155, 3, v151
	v_and_b32_e32 v156, 7, v151
	v_lshl_add_u32 v160, v155, 7, v160
	v_lshl_add_u32 v160, v156, 4, v160
	v_lshlrev_b32_e32 v158, 3, v154
	v_sub_u32_e32 v158, v149, v158
	v_lshrrev_b32_e32 v157, 5, v151
	v_lshl_add_u32 v158, v157, 3, v158
	v_and_b32_e32 v157, 3, v155
	v_add_u32_e32 v158, v158, v157
	v_mul_lo_u32 v158, v158, s36
	v_sub_u32_e32 v157, v144, v153
	v_add_u32_e32 v157, s39, v157
	v_lshl_add_u32 v157, v156, 3, v157
	v_add_u32_e32 v158, v158, v157
	v_lshlrev_b32_e32 v158, 1, v158
	v_mov_b32_e32 v159, 0
	v_lshl_add_u64 v[170:171], s[48:49], 0, v[158:159]
	s_mov_b32 s99, 0
	v_cvt_pk_bf16_f32 v150, v126, v127
	v_cvt_pk_bf16_f32 v151, v128, v129
	ds_write_b16 v161, v150
	ds_write_b16_d16_hi v161, v150 offset:128
	ds_write_b16 v161, v151 offset:256
	ds_write_b16_d16_hi v161, v151 offset:384
	v_cvt_pk_bf16_f32 v150, v110, v111
	v_cvt_pk_bf16_f32 v151, v112, v113
	ds_write_b16 v161, v150 offset:32
	ds_write_b16_d16_hi v161, v150 offset:160
	ds_write_b16 v161, v151 offset:288
	ds_write_b16_d16_hi v161, v151 offset:416
	v_cvt_pk_bf16_f32 v150, v94, v95
	v_cvt_pk_bf16_f32 v151, v96, v97
	ds_write_b16 v161, v150 offset:64
	ds_write_b16_d16_hi v161, v150 offset:192
	ds_write_b16 v161, v151 offset:320
	ds_write_b16_d16_hi v161, v151 offset:448
	v_cvt_pk_bf16_f32 v150, v78, v79
	v_cvt_pk_bf16_f32 v151, v80, v81
	ds_write_b16 v161, v150 offset:96
	ds_write_b16_d16_hi v161, v150 offset:224
	ds_write_b16 v161, v151 offset:352
	ds_write_b16_d16_hi v161, v151 offset:480
	s_waitcnt lgkmcnt(0)
	ds_read_b128 v[152:155], v160
	ds_read_b128 v[156:159], v160 offset:1024
	s_mul_i32 s98, s36, 0
	v_lshl_add_u64 v[172:173], v[170:171], 0, s[98:99]
	s_mul_i32 s98, s36, 32
	v_lshl_add_u64 v[174:175], v[170:171], 0, s[98:99]
	s_waitcnt lgkmcnt(0)
	global_store_dwordx4 v[172:173], v[152:155], off
	global_store_dwordx4 v[174:175], v[156:159], off
	v_cvt_pk_bf16_f32 v150, v122, v123
	v_cvt_pk_bf16_f32 v151, v124, v125
	ds_write_b16 v161, v150
	ds_write_b16_d16_hi v161, v150 offset:128
	ds_write_b16 v161, v151 offset:256
	ds_write_b16_d16_hi v161, v151 offset:384
	v_cvt_pk_bf16_f32 v150, v106, v107
	v_cvt_pk_bf16_f32 v151, v108, v109
	ds_write_b16 v161, v150 offset:32
	ds_write_b16_d16_hi v161, v150 offset:160
	ds_write_b16 v161, v151 offset:288
	ds_write_b16_d16_hi v161, v151 offset:416
	v_cvt_pk_bf16_f32 v150, v90, v91
	v_cvt_pk_bf16_f32 v151, v92, v93
	ds_write_b16 v161, v150 offset:64
	ds_write_b16_d16_hi v161, v150 offset:192
	ds_write_b16 v161, v151 offset:320
	ds_write_b16_d16_hi v161, v151 offset:448
	v_cvt_pk_bf16_f32 v150, v74, v75
	v_cvt_pk_bf16_f32 v151, v76, v77
	ds_write_b16 v161, v150 offset:96
	ds_write_b16_d16_hi v161, v150 offset:224
	ds_write_b16 v161, v151 offset:352
	ds_write_b16_d16_hi v161, v151 offset:480
	s_waitcnt lgkmcnt(0)
	ds_read_b128 v[152:155], v160
	ds_read_b128 v[156:159], v160 offset:1024
	s_mul_i32 s98, s36, 8
	v_lshl_add_u64 v[172:173], v[170:171], 0, s[98:99]
	s_mul_i32 s98, s36, 40
	v_lshl_add_u64 v[174:175], v[170:171], 0, s[98:99]
	s_waitcnt lgkmcnt(0)
	global_store_dwordx4 v[172:173], v[152:155], off
	global_store_dwordx4 v[174:175], v[156:159], off
	v_cvt_pk_bf16_f32 v150, v118, v119
	v_cvt_pk_bf16_f32 v151, v120, v121
	ds_write_b16 v161, v150
	ds_write_b16_d16_hi v161, v150 offset:128
	ds_write_b16 v161, v151 offset:256
	ds_write_b16_d16_hi v161, v151 offset:384
	v_cvt_pk_bf16_f32 v150, v102, v103
	v_cvt_pk_bf16_f32 v151, v104, v105
	ds_write_b16 v161, v150 offset:32
	ds_write_b16_d16_hi v161, v150 offset:160
	ds_write_b16 v161, v151 offset:288
	ds_write_b16_d16_hi v161, v151 offset:416
	v_cvt_pk_bf16_f32 v150, v86, v87
	v_cvt_pk_bf16_f32 v151, v88, v89
	ds_write_b16 v161, v150 offset:64
	ds_write_b16_d16_hi v161, v150 offset:192
	ds_write_b16 v161, v151 offset:320
	ds_write_b16_d16_hi v161, v151 offset:448
	v_cvt_pk_bf16_f32 v150, v70, v71
	v_cvt_pk_bf16_f32 v151, v72, v73
	ds_write_b16 v161, v150 offset:96
	ds_write_b16_d16_hi v161, v150 offset:224
	ds_write_b16 v161, v151 offset:352
	ds_write_b16_d16_hi v161, v151 offset:480
	s_waitcnt lgkmcnt(0)
	ds_read_b128 v[152:155], v160
	ds_read_b128 v[156:159], v160 offset:1024
	s_mul_i32 s98, s36, 256
	v_lshl_add_u64 v[172:173], v[170:171], 0, s[98:99]
	s_mul_i32 s98, s36, 288
	v_lshl_add_u64 v[174:175], v[170:171], 0, s[98:99]
	s_waitcnt lgkmcnt(0)
	global_store_dwordx4 v[172:173], v[152:155], off
	global_store_dwordx4 v[174:175], v[156:159], off
	v_cvt_pk_bf16_f32 v150, v114, v115
	v_cvt_pk_bf16_f32 v151, v116, v117
	ds_write_b16 v161, v150
	ds_write_b16_d16_hi v161, v150 offset:128
	ds_write_b16 v161, v151 offset:256
	ds_write_b16_d16_hi v161, v151 offset:384
	v_cvt_pk_bf16_f32 v150, v98, v99
	v_cvt_pk_bf16_f32 v151, v100, v101
	ds_write_b16 v161, v150 offset:32
	ds_write_b16_d16_hi v161, v150 offset:160
	ds_write_b16 v161, v151 offset:288
	ds_write_b16_d16_hi v161, v151 offset:416
	v_cvt_pk_bf16_f32 v150, v82, v83
	v_cvt_pk_bf16_f32 v151, v84, v85
	ds_write_b16 v161, v150 offset:64
	ds_write_b16_d16_hi v161, v150 offset:192
	ds_write_b16 v161, v151 offset:320
	ds_write_b16_d16_hi v161, v151 offset:448
	v_cvt_pk_bf16_f32 v150, v66, v67
	v_cvt_pk_bf16_f32 v151, v68, v69
	ds_write_b16 v161, v150 offset:96
	ds_write_b16_d16_hi v161, v150 offset:224
	ds_write_b16 v161, v151 offset:352
	ds_write_b16_d16_hi v161, v151 offset:480
	s_waitcnt lgkmcnt(0)
; __device__ __forceinline__ unsigned pk2(float lo, float hi) { const v2f_t f = {lo, hi}; const v2bf_t b = __builtin_convertvector(f, v2bf_t); return __builtin_bit_cast(unsigned, b); }
;     __device__ __forceinline__ void operator()(const f32x4 (&acc)[2][2][4][2], const Unit& u, int wr, int wc, int fr, int fq) const {
;     ...
;             for (int ai = 0; ai < 2; ++ai)
; #pragma unroll
;                 for (int m = 0; m < 4; ++m) { bf16_t* tp = vb + t0 + ai * 128 + m * 16;
; #pragma unroll
;                     for (int bj = 0; bj < 2; ++bj)
; #pragma unroll
;                         for (int n = 0; n < 2; ++n) { const f32x4 v = acc[ai][bj][m][n]; const unsigned w0 = pk2(v[0], v[1]), w1 = pk2(v[2], v[3]); const size_t c = (size_t)(cb + bj * 128 + 4 * n) * tl;
;                             tp[c] = (bf16_t)w0; tp[c + tl] = (bf16_t)(w0 >> 16); tp[c + 2 * (size_t)tl] = (bf16_t)w1; tp[c + 3 * (size_t)tl] = (bf16_t)(w1 >> 16); } }
	ds_read_b128 v[152:155], v160
	ds_read_b128 v[156:159], v160 offset:1024
	s_mul_i32 s98, s36, 264
	v_lshl_add_u64 v[172:173], v[170:171], 0, s[98:99]
	s_mul_i32 s98, s36, 296
	v_lshl_add_u64 v[174:175], v[170:171], 0, s[98:99]
	s_waitcnt lgkmcnt(0)
	global_store_dwordx4 v[172:173], v[152:155], off
	global_store_dwordx4 v[174:175], v[156:159], off
	v_cvt_pk_bf16_f32 v150, v60, v61
	v_cvt_pk_bf16_f32 v151, v62, v63
	ds_write_b16 v161, v150
	ds_write_b16_d16_hi v161, v150 offset:128
	ds_write_b16 v161, v151 offset:256
	ds_write_b16_d16_hi v161, v151 offset:384
	v_cvt_pk_bf16_f32 v150, v44, v45
	v_cvt_pk_bf16_f32 v151, v46, v47
	ds_write_b16 v161, v150 offset:32
	ds_write_b16_d16_hi v161, v150 offset:160
	ds_write_b16 v161, v151 offset:288
	ds_write_b16_d16_hi v161, v151 offset:416
	v_cvt_pk_bf16_f32 v150, v28, v29
	v_cvt_pk_bf16_f32 v151, v30, v31
	ds_write_b16 v161, v150 offset:64
	ds_write_b16_d16_hi v161, v150 offset:192
	ds_write_b16 v161, v151 offset:320
	ds_write_b16_d16_hi v161, v151 offset:448
	v_cvt_pk_bf16_f32 v150, v12, v13
	v_cvt_pk_bf16_f32 v151, v14, v15
	ds_write_b16 v161, v150 offset:96
	ds_write_b16_d16_hi v161, v150 offset:224
	ds_write_b16 v161, v151 offset:352
	ds_write_b16_d16_hi v161, v151 offset:480
	s_waitcnt lgkmcnt(0)
	ds_read_b128 v[152:155], v160
	ds_read_b128 v[156:159], v160 offset:1024
	s_mul_i32 s98, s36, 0
	s_add_i32 s98, s98, 256
	v_lshl_add_u64 v[172:173], v[170:171], 0, s[98:99]
	s_mul_i32 s98, s36, 32
	s_add_i32 s98, s98, 256
	v_lshl_add_u64 v[174:175], v[170:171], 0, s[98:99]
	s_waitcnt lgkmcnt(0)
	global_store_dwordx4 v[172:173], v[152:155], off
	global_store_dwordx4 v[174:175], v[156:159], off
	v_cvt_pk_bf16_f32 v150, v56, v57
	v_cvt_pk_bf16_f32 v151, v58, v59
	ds_write_b16 v161, v150
	ds_write_b16_d16_hi v161, v150 offset:128
	ds_write_b16 v161, v151 offset:256
	ds_write_b16_d16_hi v161, v151 offset:384
	v_cvt_pk_bf16_f32 v150, v40, v41
	v_cvt_pk_bf16_f32 v151, v42, v43
	ds_write_b16 v161, v150 offset:32
	ds_write_b16_d16_hi v161, v150 offset:160
	ds_write_b16 v161, v151 offset:288
	ds_write_b16_d16_hi v161, v151 offset:416
	v_cvt_pk_bf16_f32 v150, v24, v25
	v_cvt_pk_bf16_f32 v151, v26, v27
	ds_write_b16 v161, v150 offset:64
	ds_write_b16_d16_hi v161, v150 offset:192
	ds_write_b16 v161, v151 offset:320
	ds_write_b16_d16_hi v161, v151 offset:448
	v_cvt_pk_bf16_f32 v150, v8, v9
	v_cvt_pk_bf16_f32 v151, v10, v11
	ds_write_b16 v161, v150 offset:96
	ds_write_b16_d16_hi v161, v150 offset:224
	ds_write_b16 v161, v151 offset:352
	ds_write_b16_d16_hi v161, v151 offset:480
	s_waitcnt lgkmcnt(0)
	ds_read_b128 v[152:155], v160
	ds_read_b128 v[156:159], v160 offset:1024
	s_mul_i32 s98, s36, 8
	s_add_i32 s98, s98, 256
	v_lshl_add_u64 v[172:173], v[170:171], 0, s[98:99]
	s_mul_i32 s98, s36, 40
	s_add_i32 s98, s98, 256
	v_lshl_add_u64 v[174:175], v[170:171], 0, s[98:99]
	s_waitcnt lgkmcnt(0)
	global_store_dwordx4 v[172:173], v[152:155], off
	global_store_dwordx4 v[174:175], v[156:159], off
	v_cvt_pk_bf16_f32 v150, v52, v53
	v_cvt_pk_bf16_f32 v151, v54, v55
	ds_write_b16 v161, v150
	ds_write_b16_d16_hi v161, v150 offset:128
	ds_write_b16 v161, v151 offset:256
	ds_write_b16_d16_hi v161, v151 offset:384
	v_cvt_pk_bf16_f32 v150, v36, v37
	v_cvt_pk_bf16_f32 v151, v38, v39
	ds_write_b16 v161, v150 offset:32
	ds_write_b16_d16_hi v161, v150 offset:160
	ds_write_b16 v161, v151 offset:288
	ds_write_b16_d16_hi v161, v151 offset:416
	v_cvt_pk_bf16_f32 v150, v20, v21
	v_cvt_pk_bf16_f32 v151, v22, v23
	ds_write_b16 v161, v150 offset:64
	ds_write_b16_d16_hi v161, v150 offset:192
	ds_write_b16 v161, v151 offset:320
	ds_write_b16_d16_hi v161, v151 offset:448
	v_cvt_pk_bf16_f32 v150, v4, v5
	v_cvt_pk_bf16_f32 v151, v6, v7
	ds_write_b16 v161, v150 offset:96
	ds_write_b16_d16_hi v161, v150 offset:224
	ds_write_b16 v161, v151 offset:352
	ds_write_b16_d16_hi v161, v151 offset:480
	s_waitcnt lgkmcnt(0)
	ds_read_b128 v[152:155], v160
	ds_read_b128 v[156:159], v160 offset:1024
	s_mul_i32 s98, s36, 256
	s_add_i32 s98, s98, 256
	v_lshl_add_u64 v[172:173], v[170:171], 0, s[98:99]
	s_mul_i32 s98, s36, 288
	s_add_i32 s98, s98, 256
	v_lshl_add_u64 v[174:175], v[170:171], 0, s[98:99]
	s_waitcnt lgkmcnt(0)
	global_store_dwordx4 v[172:173], v[152:155], off
	global_store_dwordx4 v[174:175], v[156:159], off
	v_cvt_pk_bf16_f32 v150, v48, v49
	v_cvt_pk_bf16_f32 v151, v50, v51
	ds_write_b16 v161, v150
	ds_write_b16_d16_hi v161, v150 offset:128
	ds_write_b16 v161, v151 offset:256
	ds_write_b16_d16_hi v161, v151 offset:384
	v_cvt_pk_bf16_f32 v150, v32, v33
	v_cvt_pk_bf16_f32 v151, v34, v35
	ds_write_b16 v161, v150 offset:32
	ds_write_b16_d16_hi v161, v150 offset:160
	ds_write_b16 v161, v151 offset:288
	ds_write_b16_d16_hi v161, v151 offset:416
	v_cvt_pk_bf16_f32 v150, v16, v17
	v_cvt_pk_bf16_f32 v151, v18, v19
	ds_write_b16 v161, v150 offset:64
	ds_write_b16_d16_hi v161, v150 offset:192
	ds_write_b16 v161, v151 offset:320
	ds_write_b16_d16_hi v161, v151 offset:448
	v_cvt_pk_bf16_f32 v150, v0, v1
	v_cvt_pk_bf16_f32 v151, v2, v3
	ds_write_b16 v161, v150 offset:96
	ds_write_b16_d16_hi v161, v150 offset:224
	ds_write_b16 v161, v151 offset:352
	ds_write_b16_d16_hi v161, v151 offset:480
	s_waitcnt lgkmcnt(0)
	ds_read_b128 v[152:155], v160
	ds_read_b128 v[156:159], v160 offset:1024
	s_mul_i32 s98, s36, 264
	s_add_i32 s98, s98, 256
	v_lshl_add_u64 v[172:173], v[170:171], 0, s[98:99]
	s_mul_i32 s98, s36, 296
	s_add_i32 s98, s98, 256
	v_lshl_add_u64 v[174:175], v[170:171], 0, s[98:99]
	s_waitcnt lgkmcnt(0)
	global_store_dwordx4 v[172:173], v[152:155], off
	global_store_dwordx4 v[174:175], v[156:159], off
